# v15 + mLSTM stage C: state rows staged per wave through a private LDS ring by LDS-DMA (whole 128B lines, swizzled), Q operand prefetched one group ahead
# speedup vs baseline: 1.0113x; 1.0063x over previous
; __device__ __forceinline__ void mlstm_stage_c(LAS unsigned char* lds, const bf16_t* QKO, const bf16_t* KVT, const float* G, const float* gbias, const bf16_t* DC, const float* DN, ...
;     ...
;         { const bf16_t* q0p = QKO + (size_t)(t0 + r32) * 4096 + h * 256 + hi * 8; const bf16_t* q1p = q0p + (size_t)32 * 4096;
;           const bf16_t* s0p = DC + ((size_t)((c * 4 + h) * 512 + wave * 64 + r32)) * 256 + hi * 8; const bf16_t* s1p = s0p + 32 * 256;
; #pragma unroll
;           for (int ks = 0; ks < 16; ++ks) { const bf16x8 b0 = *(const bf16x8*)(q0p + ks * 16), b1 = *(const bf16x8*)(q1p + ks * 16);
;               const bf16x8 a0 = *(const bf16x8*)(s0p + ks * 16), a1 = *(const bf16x8*)(s1p + ks * 16);
;               acc[0][0] = __builtin_amdgcn_mfma_f32_32x32x16_bf16(a0, b0, acc[0][0], 0, 0, 0); acc[0][1] = __builtin_amdgcn_mfma_f32_32x32x16_bf16(a0, b1, acc[0][1], 0, 0, 0);
;               acc[1][0] = __builtin_amdgcn_mfma_f32_32x32x16_bf16(a1, b0, acc[1][0], 0, 0, 0); acc[1][1] = __builtin_amdgcn_mfma_f32_32x32x16_bf16(a1, b1, acc[1][1], 0, 0, 0); } }
.LBB0_822:
	v_or_b32_e32 v80, s18, v113
	v_ashrrev_i32_e32 v81, 31, v80
	v_readlane_b32 s0, v249, 58
	v_lshlrev_b64 v[0:1], 13, v[80:81]
	v_readlane_b32 s1, v249, 59
	v_ashrrev_i32_e32 v77, 31, v76
	s_ashr_i32 s19, s18, 31
	v_lshl_add_u64 v[82:83], s[0:1], 0, v[0:1]
	s_lshl_b32 s0, s4, 1
	s_mov_b32 s1, s21
	v_lshl_add_u64 v[0:1], v[82:83], 0, s[0:1]
	v_lshl_add_u64 v[86:87], v[0:1], 0, v[68:69]
	s_mov_b32 s0, 0x40000
	v_lshlrev_b64 v[0:1], 9, v[76:77]
	v_add_co_u32_e32 v90, vcc, s0, v86
	v_lshl_add_u64 v[84:85], v[72:73], 0, v[0:1]
	s_nop 0
	v_addc_co_u32_e32 v91, vcc, 0, v87, vcc
	s_movk_i32 s0, 0x4000
	v_add_co_u32_e32 v88, vcc, s0, v84
	s_nop 0
	v_addc_co_u32_e32 v89, vcc, 0, v85, vcc
	v_and_b32_e32 v247, 63, v204
	v_lshrrev_b32_e32 v246, 6, v204
	v_lshlrev_b32_e32 v246, 14, v246
	v_add_u32_e32 v246, 0x3c00, v246
	v_readfirstlane_b32 s100, v84
	v_readfirstlane_b32 s101, v85
	v_readfirstlane_b32 s98, v246
	s_nop 3
	v_lshrrev_b32_e32 v240, 4, v247
	v_and_b32_e32 v241, 7, v247
	v_xor_b32_e32 v242, v240, v241
	v_lshlrev_b32_e32 v242, 4, v242
	v_lshrrev_b32_e32 v243, 3, v247
	v_lshl_add_u32 v244, v243, 9, v242
	v_mov_b32_e32 v245, 0
	v_lshl_add_u64 v[236:237], s[100:101], 0, v[244:245]
	v_or_b32_e32 v240, 4, v240
	v_xor_b32_e32 v242, v240, v241
	v_lshlrev_b32_e32 v242, 4, v242
	v_lshl_add_u32 v244, v243, 9, v242
	v_add_u32_e32 v244, 0x1000, v244
	v_lshl_add_u64 v[238:239], s[100:101], 0, v[244:245]
	v_and_b32_e32 v244, 31, v247
	v_bfe_u32 v245, v247, 1, 3
	v_lshl_add_u32 v246, v244, 7, v246
	v_lshrrev_b32_e32 v244, 5, v247
	v_or_b32_e32 v240, 0, v244
	v_xor_b32_e32 v240, v240, v245
	v_lshl_add_u32 v240, v240, 4, v246
	v_or_b32_e32 v241, 2, v244
	v_xor_b32_e32 v241, v241, v245
	v_lshl_add_u32 v241, v241, 4, v246
	v_or_b32_e32 v242, 4, v244
	v_xor_b32_e32 v242, v242, v245
	v_lshl_add_u32 v242, v242, 4, v246
	v_or_b32_e32 v243, 6, v244
	v_xor_b32_e32 v243, v243, v245
	v_lshl_add_u32 v243, v243, 4, v246
	s_mov_b64 s[100:101], 0x0
	v_lshl_add_u64 v[244:245], v[236:237], 0, s[100:101]
	s_add_i32 m0, s98, 0x0
	s_nop 0
	global_load_lds_dwordx4 v[244:245], off
	s_mov_b64 s[100:101], 0x0
	v_lshl_add_u64 v[244:245], v[238:239], 0, s[100:101]
	s_add_i32 m0, s98, 0x400
	s_nop 0
	global_load_lds_dwordx4 v[244:245], off
	s_mov_b64 s[100:101], 0x2000
	v_lshl_add_u64 v[244:245], v[236:237], 0, s[100:101]
	s_add_i32 m0, s98, 0x800
	s_nop 0
	global_load_lds_dwordx4 v[244:245], off
	s_mov_b64 s[100:101], 0x2000
	v_lshl_add_u64 v[244:245], v[238:239], 0, s[100:101]
	s_add_i32 m0, s98, 0xc00
	s_nop 0
	global_load_lds_dwordx4 v[244:245], off
	s_mov_b64 s[100:101], 0x4000
	v_lshl_add_u64 v[244:245], v[236:237], 0, s[100:101]
	s_add_i32 m0, s98, 0x1000
	s_nop 0
	global_load_lds_dwordx4 v[244:245], off
	s_mov_b64 s[100:101], 0x4000
	v_lshl_add_u64 v[244:245], v[238:239], 0, s[100:101]
	s_add_i32 m0, s98, 0x1400
	s_nop 0
	global_load_lds_dwordx4 v[244:245], off
	s_mov_b64 s[100:101], 0x6000
	v_lshl_add_u64 v[244:245], v[236:237], 0, s[100:101]
	s_add_i32 m0, s98, 0x1800
	s_nop 0
	global_load_lds_dwordx4 v[244:245], off
	s_mov_b64 s[100:101], 0x6000
	v_lshl_add_u64 v[244:245], v[238:239], 0, s[100:101]
	s_add_i32 m0, s98, 0x1c00
	s_nop 0
	global_load_lds_dwordx4 v[244:245], off
	global_load_dwordx4 v[152:155], v[86:87], off
	global_load_dwordx4 v[156:159], v[90:91], off
	global_load_dwordx4 v[160:163], v[86:87], off offset:32
	global_load_dwordx4 v[164:167], v[90:91], off offset:32
	global_load_dwordx4 v[168:171], v[86:87], off offset:64
	global_load_dwordx4 v[172:175], v[90:91], off offset:64
	global_load_dwordx4 v[176:179], v[86:87], off offset:96
	global_load_dwordx4 v[180:183], v[90:91], off offset:96
	s_mov_b64 s[100:101], 0x80
	v_lshl_add_u64 v[244:245], v[236:237], 0, s[100:101]
	s_add_i32 m0, s98, 0x2000
	s_nop 0
	global_load_lds_dwordx4 v[244:245], off
	s_mov_b64 s[100:101], 0x80
	v_lshl_add_u64 v[244:245], v[238:239], 0, s[100:101]
	s_add_i32 m0, s98, 0x2400
	s_nop 0
	global_load_lds_dwordx4 v[244:245], off
	s_mov_b64 s[100:101], 0x2080
	v_lshl_add_u64 v[244:245], v[236:237], 0, s[100:101]
	s_add_i32 m0, s98, 0x2800
	s_nop 0
	global_load_lds_dwordx4 v[244:245], off
	s_mov_b64 s[100:101], 0x2080
	v_lshl_add_u64 v[244:245], v[238:239], 0, s[100:101]
	s_add_i32 m0, s98, 0x2c00
	s_nop 0
	global_load_lds_dwordx4 v[244:245], off
	s_mov_b64 s[100:101], 0x4080
	v_lshl_add_u64 v[244:245], v[236:237], 0, s[100:101]
	s_add_i32 m0, s98, 0x3000
	s_nop 0
	global_load_lds_dwordx4 v[244:245], off
	s_mov_b64 s[100:101], 0x4080
	v_lshl_add_u64 v[244:245], v[238:239], 0, s[100:101]
	s_add_i32 m0, s98, 0x3400
	s_nop 0
	global_load_lds_dwordx4 v[244:245], off
	s_mov_b64 s[100:101], 0x6080
	v_lshl_add_u64 v[244:245], v[236:237], 0, s[100:101]
	s_add_i32 m0, s98, 0x3800
	s_nop 0
	global_load_lds_dwordx4 v[244:245], off
	s_mov_b64 s[100:101], 0x6080
	v_lshl_add_u64 v[244:245], v[238:239], 0, s[100:101]
	s_add_i32 m0, s98, 0x3c00
	s_nop 0
	global_load_lds_dwordx4 v[244:245], off
	global_load_dwordx4 v[184:187], v[86:87], off offset:128
	global_load_dwordx4 v[188:191], v[90:91], off offset:128
	global_load_dwordx4 v[192:195], v[86:87], off offset:160
	global_load_dwordx4 v[196:199], v[90:91], off offset:160
	global_load_dwordx4 v[200:203], v[86:87], off offset:192
	global_load_dwordx4 v[208:211], v[90:91], off offset:192
	global_load_dwordx4 v[212:215], v[86:87], off offset:224
	global_load_dwordx4 v[216:219], v[90:91], off offset:224
	v_readlane_b32 s0, v249, 46
	v_readlane_b32 s1, v249, 47
	v_add_u32_e32 v77, v122, v70
	s_waitcnt vmcnt(16)
	ds_read_b128 v[220:223], v240 offset:0
	ds_read_b128 v[224:227], v240 offset:4096
	ds_read_b128 v[228:231], v241 offset:0
	ds_read_b128 v[232:235], v241 offset:4096
	s_waitcnt lgkmcnt(2)
; __device__ __forceinline__ void mlstm_stage_c(LAS unsigned char* lds, const bf16_t* QKO, const bf16_t* KVT, const float* G, const float* gbias, const bf16_t* DC, const float* DN, ...
;     ...
;         { const bf16_t* q0p = QKO + (size_t)(t0 + r32) * 4096 + h * 256 + hi * 8; const bf16_t* q1p = q0p + (size_t)32 * 4096;
;           const bf16_t* s0p = DC + ((size_t)((c * 4 + h) * 512 + wave * 64 + r32)) * 256 + hi * 8; const bf16_t* s1p = s0p + 32 * 256;
; #pragma unroll
;           for (int ks = 0; ks < 16; ++ks) { const bf16x8 b0 = *(const bf16x8*)(q0p + ks * 16), b1 = *(const bf16x8*)(q1p + ks * 16);
;               const bf16x8 a0 = *(const bf16x8*)(s0p + ks * 16), a1 = *(const bf16x8*)(s1p + ks * 16);
;               acc[0][0] = __builtin_amdgcn_mfma_f32_32x32x16_bf16(a0, b0, acc[0][0], 0, 0, 0); acc[0][1] = __builtin_amdgcn_mfma_f32_32x32x16_bf16(a0, b1, acc[0][1], 0, 0, 0);
;               acc[1][0] = __builtin_amdgcn_mfma_f32_32x32x16_bf16(a1, b0, acc[1][0], 0, 0, 0); acc[1][1] = __builtin_amdgcn_mfma_f32_32x32x16_bf16(a1, b1, acc[1][1], 0, 0, 0); } }
	v_mfma_f32_32x32x16_bf16 v[48:63], v[220:223], v[152:155], 0
	v_mfma_f32_32x32x16_bf16 v[32:47], v[220:223], v[156:159], 0
	v_mfma_f32_32x32x16_bf16 v[16:31], v[224:227], v[152:155], 0
	v_mfma_f32_32x32x16_bf16 v[0:15], v[224:227], v[156:159], 0
	ds_read_b128 v[220:223], v242 offset:0
	ds_read_b128 v[224:227], v242 offset:4096
	s_waitcnt lgkmcnt(2)
	v_mfma_f32_32x32x16_bf16 v[48:63], v[228:231], v[160:163], v[48:63]
	v_mfma_f32_32x32x16_bf16 v[32:47], v[228:231], v[164:167], v[32:47]
	v_mfma_f32_32x32x16_bf16 v[16:31], v[232:235], v[160:163], v[16:31]
	v_mfma_f32_32x32x16_bf16 v[0:15], v[232:235], v[164:167], v[0:15]
	ds_read_b128 v[228:231], v243 offset:0
	ds_read_b128 v[232:235], v243 offset:4096
	s_waitcnt lgkmcnt(2)
	v_mfma_f32_32x32x16_bf16 v[48:63], v[220:223], v[168:171], v[48:63]
	v_mfma_f32_32x32x16_bf16 v[32:47], v[220:223], v[172:175], v[32:47]
	v_mfma_f32_32x32x16_bf16 v[16:31], v[224:227], v[168:171], v[16:31]
	v_mfma_f32_32x32x16_bf16 v[0:15], v[224:227], v[172:175], v[0:15]
	s_waitcnt lgkmcnt(0)
	v_mfma_f32_32x32x16_bf16 v[48:63], v[228:231], v[176:179], v[48:63]
	v_mfma_f32_32x32x16_bf16 v[32:47], v[228:231], v[180:183], v[32:47]
	v_mfma_f32_32x32x16_bf16 v[16:31], v[232:235], v[176:179], v[16:31]
	v_mfma_f32_32x32x16_bf16 v[0:15], v[232:235], v[180:183], v[0:15]
	s_mov_b64 s[100:101], 0x100
	v_lshl_add_u64 v[244:245], v[236:237], 0, s[100:101]
	s_add_i32 m0, s98, 0x0
	s_nop 0
	global_load_lds_dwordx4 v[244:245], off
	s_mov_b64 s[100:101], 0x100
	v_lshl_add_u64 v[244:245], v[238:239], 0, s[100:101]
	s_add_i32 m0, s98, 0x400
	s_nop 0
	global_load_lds_dwordx4 v[244:245], off
	s_mov_b64 s[100:101], 0x2100
	v_lshl_add_u64 v[244:245], v[236:237], 0, s[100:101]
	s_add_i32 m0, s98, 0x800
	s_nop 0
	global_load_lds_dwordx4 v[244:245], off
	s_mov_b64 s[100:101], 0x2100
	v_lshl_add_u64 v[244:245], v[238:239], 0, s[100:101]
	s_add_i32 m0, s98, 0xc00
	s_nop 0
	global_load_lds_dwordx4 v[244:245], off
	s_mov_b64 s[100:101], 0x4100
	v_lshl_add_u64 v[244:245], v[236:237], 0, s[100:101]
	s_add_i32 m0, s98, 0x1000
	s_nop 0
	global_load_lds_dwordx4 v[244:245], off
	s_mov_b64 s[100:101], 0x4100
	v_lshl_add_u64 v[244:245], v[238:239], 0, s[100:101]
	s_add_i32 m0, s98, 0x1400
	s_nop 0
	global_load_lds_dwordx4 v[244:245], off
	s_mov_b64 s[100:101], 0x6100
	v_lshl_add_u64 v[244:245], v[236:237], 0, s[100:101]
	s_add_i32 m0, s98, 0x1800
	s_nop 0
	global_load_lds_dwordx4 v[244:245], off
	s_mov_b64 s[100:101], 0x6100
	v_lshl_add_u64 v[244:245], v[238:239], 0, s[100:101]
	s_add_i32 m0, s98, 0x1c00
	s_nop 0
	global_load_lds_dwordx4 v[244:245], off
	global_load_dwordx4 v[152:155], v[86:87], off offset:256
	global_load_dwordx4 v[156:159], v[90:91], off offset:256
	global_load_dwordx4 v[160:163], v[86:87], off offset:288
	global_load_dwordx4 v[164:167], v[90:91], off offset:288
	global_load_dwordx4 v[168:171], v[86:87], off offset:320
	global_load_dwordx4 v[172:175], v[90:91], off offset:320
	global_load_dwordx4 v[176:179], v[86:87], off offset:352
	global_load_dwordx4 v[180:183], v[90:91], off offset:352
	s_waitcnt vmcnt(16)
	ds_read_b128 v[220:223], v240 offset:8192
	ds_read_b128 v[224:227], v240 offset:12288
	ds_read_b128 v[228:231], v241 offset:8192
	ds_read_b128 v[232:235], v241 offset:12288
	s_waitcnt lgkmcnt(2)
	v_mfma_f32_32x32x16_bf16 v[48:63], v[220:223], v[184:187], v[48:63]
	v_mfma_f32_32x32x16_bf16 v[32:47], v[220:223], v[188:191], v[32:47]
	v_mfma_f32_32x32x16_bf16 v[16:31], v[224:227], v[184:187], v[16:31]
	v_mfma_f32_32x32x16_bf16 v[0:15], v[224:227], v[188:191], v[0:15]
	ds_read_b128 v[220:223], v242 offset:8192
	ds_read_b128 v[224:227], v242 offset:12288
	s_waitcnt lgkmcnt(2)
	v_mfma_f32_32x32x16_bf16 v[48:63], v[228:231], v[192:195], v[48:63]
	v_mfma_f32_32x32x16_bf16 v[32:47], v[228:231], v[196:199], v[32:47]
	v_mfma_f32_32x32x16_bf16 v[16:31], v[232:235], v[192:195], v[16:31]
	v_mfma_f32_32x32x16_bf16 v[0:15], v[232:235], v[196:199], v[0:15]
	ds_read_b128 v[228:231], v243 offset:8192
	ds_read_b128 v[232:235], v243 offset:12288
	s_waitcnt lgkmcnt(2)
	v_mfma_f32_32x32x16_bf16 v[48:63], v[220:223], v[200:203], v[48:63]
	v_mfma_f32_32x32x16_bf16 v[32:47], v[220:223], v[208:211], v[32:47]
	v_mfma_f32_32x32x16_bf16 v[16:31], v[224:227], v[200:203], v[16:31]
	v_mfma_f32_32x32x16_bf16 v[0:15], v[224:227], v[208:211], v[0:15]
	s_waitcnt lgkmcnt(0)
	v_mfma_f32_32x32x16_bf16 v[48:63], v[228:231], v[212:215], v[48:63]
	v_mfma_f32_32x32x16_bf16 v[32:47], v[228:231], v[216:219], v[32:47]
	v_mfma_f32_32x32x16_bf16 v[16:31], v[232:235], v[212:215], v[16:31]
	v_mfma_f32_32x32x16_bf16 v[0:15], v[232:235], v[216:219], v[0:15]
	s_mov_b64 s[100:101], 0x180
	v_lshl_add_u64 v[244:245], v[236:237], 0, s[100:101]
	s_add_i32 m0, s98, 0x2000
	s_nop 0
	global_load_lds_dwordx4 v[244:245], off
	s_mov_b64 s[100:101], 0x180
	v_lshl_add_u64 v[244:245], v[238:239], 0, s[100:101]
	s_add_i32 m0, s98, 0x2400
	s_nop 0
	global_load_lds_dwordx4 v[244:245], off
	s_mov_b64 s[100:101], 0x2180
	v_lshl_add_u64 v[244:245], v[236:237], 0, s[100:101]
	s_add_i32 m0, s98, 0x2800
	s_nop 0
	global_load_lds_dwordx4 v[244:245], off
	s_mov_b64 s[100:101], 0x2180
	v_lshl_add_u64 v[244:245], v[238:239], 0, s[100:101]
	s_add_i32 m0, s98, 0x2c00
	s_nop 0
	global_load_lds_dwordx4 v[244:245], off
	s_mov_b64 s[100:101], 0x4180
	v_lshl_add_u64 v[244:245], v[236:237], 0, s[100:101]
	s_add_i32 m0, s98, 0x3000
	s_nop 0
	global_load_lds_dwordx4 v[244:245], off
	s_mov_b64 s[100:101], 0x4180
	v_lshl_add_u64 v[244:245], v[238:239], 0, s[100:101]
	s_add_i32 m0, s98, 0x3400
	s_nop 0
	global_load_lds_dwordx4 v[244:245], off
	s_mov_b64 s[100:101], 0x6180
	v_lshl_add_u64 v[244:245], v[236:237], 0, s[100:101]
	s_add_i32 m0, s98, 0x3800
	s_nop 0
	global_load_lds_dwordx4 v[244:245], off
	s_mov_b64 s[100:101], 0x6180
	v_lshl_add_u64 v[244:245], v[238:239], 0, s[100:101]
	s_add_i32 m0, s98, 0x3c00
	s_nop 0
	global_load_lds_dwordx4 v[244:245], off
	global_load_dwordx4 v[184:187], v[86:87], off offset:384
	global_load_dwordx4 v[188:191], v[90:91], off offset:384
	global_load_dwordx4 v[192:195], v[86:87], off offset:416
	global_load_dwordx4 v[196:199], v[90:91], off offset:416
	global_load_dwordx4 v[200:203], v[86:87], off offset:448
	global_load_dwordx4 v[208:211], v[90:91], off offset:448
	global_load_dwordx4 v[212:215], v[86:87], off offset:480
	global_load_dwordx4 v[216:219], v[90:91], off offset:480
	s_waitcnt vmcnt(16)
; #define LAS __attribute__((address_space(3)))
; __device__ __forceinline__ void mlstm_stage_c(LAS unsigned char* lds, const bf16_t* QKO, const bf16_t* KVT, const float* G, const float* gbias, const bf16_t* DC, const float* DN, ...
;     ...
; #pragma unroll
;           for (int ks = 0; ks < 16; ++ks) { const bf16x8 b0 = *(const bf16x8*)(q0p + ks * 16), b1 = *(const bf16x8*)(q1p + ks * 16);
;               const bf16x8 a0 = *(const bf16x8*)(s0p + ks * 16), a1 = *(const bf16x8*)(s1p + ks * 16);
;               acc[0][0] = __builtin_amdgcn_mfma_f32_32x32x16_bf16(a0, b0, acc[0][0], 0, 0, 0); acc[0][1] = __builtin_amdgcn_mfma_f32_32x32x16_bf16(a0, b1, acc[0][1], 0, 0, 0);
;               acc[1][0] = __builtin_amdgcn_mfma_f32_32x32x16_bf16(a1, b0, acc[1][0], 0, 0, 0); acc[1][1] = __builtin_amdgcn_mfma_f32_32x32x16_bf16(a1, b1, acc[1][1], 0, 0, 0); } }
;         { const float a0 = sA[r32], a1 = sA[32 + r32];
; #pragma unroll
;           for (int vb = 0; vb < 2; ++vb) { acc[vb][0] *= a0; acc[vb][1] *= a1; } }
;         { const bf16_t* v0p = KVT + (size_t)(h * 512 + wave * 64 + r32) * M + t0 + hi * 8; const bf16_t* v1p = v0p + (size_t)32 * M;
; #pragma unroll
;           for (int ks = 0; ks < 4; ++ks) { const bf16x8 b0 = *(const LAS bf16x8*)(sW + r32 * 144 + ks * 32 + hi * 16), b1 = *(const LAS bf16x8*)(sW + (32 + r32) * 144 + ks * 32 + hi * 16);
;               const bf16x8 a0 = *(const bf16x8*)(v0p + ks * 16), a1 = *(const bf16x8*)(v1p + ks * 16);
;               acc[0][0] = __builtin_amdgcn_mfma_f32_32x32x16_bf16(a0, b0, acc[0][0], 0, 0, 0); acc[0][1] = __builtin_amdgcn_mfma_f32_32x32x16_bf16(a0, b1, acc[0][1], 0, 0, 0);
;               acc[1][0] = __builtin_amdgcn_mfma_f32_32x32x16_bf16(a1, b0, acc[1][0], 0, 0, 0); acc[1][1] = __builtin_amdgcn_mfma_f32_32x32x16_bf16(a1, b1, acc[1][1], 0, 0, 0); } }
	ds_read_b128 v[220:223], v240 offset:0
	ds_read_b128 v[224:227], v240 offset:4096
	ds_read_b128 v[228:231], v241 offset:0
	ds_read_b128 v[232:235], v241 offset:4096
	s_waitcnt lgkmcnt(2)
	v_mfma_f32_32x32x16_bf16 v[48:63], v[220:223], v[152:155], v[48:63]
	v_mfma_f32_32x32x16_bf16 v[32:47], v[220:223], v[156:159], v[32:47]
	v_mfma_f32_32x32x16_bf16 v[16:31], v[224:227], v[152:155], v[16:31]
	v_mfma_f32_32x32x16_bf16 v[0:15], v[224:227], v[156:159], v[0:15]
	ds_read_b128 v[220:223], v242 offset:0
	ds_read_b128 v[224:227], v242 offset:4096
	s_waitcnt lgkmcnt(2)
	v_mfma_f32_32x32x16_bf16 v[48:63], v[228:231], v[160:163], v[48:63]
	v_mfma_f32_32x32x16_bf16 v[32:47], v[228:231], v[164:167], v[32:47]
	v_mfma_f32_32x32x16_bf16 v[16:31], v[232:235], v[160:163], v[16:31]
	v_mfma_f32_32x32x16_bf16 v[0:15], v[232:235], v[164:167], v[0:15]
	ds_read_b128 v[228:231], v243 offset:0
	ds_read_b128 v[232:235], v243 offset:4096
	s_waitcnt lgkmcnt(2)
	v_mfma_f32_32x32x16_bf16 v[48:63], v[220:223], v[168:171], v[48:63]
	v_mfma_f32_32x32x16_bf16 v[32:47], v[220:223], v[172:175], v[32:47]
	v_mfma_f32_32x32x16_bf16 v[16:31], v[224:227], v[168:171], v[16:31]
	v_mfma_f32_32x32x16_bf16 v[0:15], v[224:227], v[172:175], v[0:15]
	s_waitcnt lgkmcnt(0)
	v_mfma_f32_32x32x16_bf16 v[48:63], v[228:231], v[176:179], v[48:63]
	v_mfma_f32_32x32x16_bf16 v[32:47], v[228:231], v[180:183], v[32:47]
	v_mfma_f32_32x32x16_bf16 v[16:31], v[232:235], v[176:179], v[16:31]
	v_mfma_f32_32x32x16_bf16 v[0:15], v[232:235], v[180:183], v[0:15]
	s_waitcnt vmcnt(0)
	ds_read_b128 v[220:223], v240 offset:8192
	ds_read_b128 v[224:227], v240 offset:12288
	ds_read_b128 v[228:231], v241 offset:8192
	ds_read_b128 v[232:235], v241 offset:12288
	s_waitcnt lgkmcnt(2)
	v_mfma_f32_32x32x16_bf16 v[48:63], v[220:223], v[184:187], v[48:63]
	v_mfma_f32_32x32x16_bf16 v[32:47], v[220:223], v[188:191], v[32:47]
	v_mfma_f32_32x32x16_bf16 v[16:31], v[224:227], v[184:187], v[16:31]
	v_mfma_f32_32x32x16_bf16 v[0:15], v[224:227], v[188:191], v[0:15]
	ds_read_b128 v[220:223], v242 offset:8192
	ds_read_b128 v[224:227], v242 offset:12288
	s_waitcnt lgkmcnt(2)
	v_mfma_f32_32x32x16_bf16 v[48:63], v[228:231], v[192:195], v[48:63]
	v_mfma_f32_32x32x16_bf16 v[32:47], v[228:231], v[196:199], v[32:47]
	v_mfma_f32_32x32x16_bf16 v[16:31], v[232:235], v[192:195], v[16:31]
	v_mfma_f32_32x32x16_bf16 v[0:15], v[232:235], v[196:199], v[0:15]
	ds_read_b128 v[228:231], v243 offset:8192
	ds_read_b128 v[232:235], v243 offset:12288
	s_waitcnt lgkmcnt(2)
	v_mfma_f32_32x32x16_bf16 v[48:63], v[220:223], v[200:203], v[48:63]
	v_mfma_f32_32x32x16_bf16 v[32:47], v[220:223], v[208:211], v[32:47]
	v_mfma_f32_32x32x16_bf16 v[16:31], v[224:227], v[200:203], v[16:31]
	v_mfma_f32_32x32x16_bf16 v[0:15], v[224:227], v[208:211], v[0:15]
	s_waitcnt lgkmcnt(0)
	v_mfma_f32_32x32x16_bf16 v[48:63], v[228:231], v[212:215], v[48:63]
	v_mfma_f32_32x32x16_bf16 v[32:47], v[228:231], v[216:219], v[32:47]
	v_mfma_f32_32x32x16_bf16 v[16:31], v[232:235], v[212:215], v[16:31]
	v_mfma_f32_32x32x16_bf16 v[0:15], v[232:235], v[216:219], v[0:15]
	s_nop 7
	ds_read2_b32 v[84:85], v114 offset0:192 offset1:224
	s_waitcnt lgkmcnt(0)
	s_nop 6
	v_mul_f32_e64 v62, v62, v84
	v_mul_f32_e64 v63, v63, v84
	v_mul_f32_e64 v60, v60, v84
	v_mul_f32_e64 v61, v61, v84
	v_mul_f32_e64 v58, v58, v84
	v_mul_f32_e64 v59, v59, v84
	v_mul_f32_e64 v56, v56, v84
	v_mul_f32_e64 v57, v57, v84
	v_mul_f32_e64 v54, v54, v84
	v_mul_f32_e64 v55, v55, v84
	v_pk_mul_f32 v[52:53], v[52:53], v[84:85] op_sel_hi:[1,0]
	v_pk_mul_f32 v[50:51], v[50:51], v[84:85] op_sel_hi:[1,0]
	v_pk_mul_f32 v[48:49], v[48:49], v[84:85] op_sel_hi:[1,0]
	v_pk_mul_f32 v[30:31], v[30:31], v[84:85] op_sel_hi:[1,0]
	v_pk_mul_f32 v[28:29], v[28:29], v[84:85] op_sel_hi:[1,0]
	v_pk_mul_f32 v[26:27], v[26:27], v[84:85] op_sel_hi:[1,0]
	v_pk_mul_f32 v[24:25], v[24:25], v[84:85] op_sel_hi:[1,0]
	v_pk_mul_f32 v[22:23], v[22:23], v[84:85] op_sel_hi:[1,0]
	v_pk_mul_f32 v[20:21], v[20:21], v[84:85] op_sel_hi:[1,0]
	v_pk_mul_f32 v[18:19], v[18:19], v[84:85] op_sel_hi:[1,0]
	v_pk_mul_f32 v[16:17], v[16:17], v[84:85] op_sel_hi:[1,0]
	v_add_u32_e32 v84, s20, v121
	v_mov_b32_e32 v86, v85
	v_ashrrev_i32_e32 v85, 31, v84
	v_lshlrev_b64 v[84:85], 15, v[84:85]
	v_lshl_add_u64 v[84:85], s[0:1], 0, v[84:85]
	v_lshl_add_u64 v[84:85], s[18:19], 1, v[84:85]
	v_pk_mul_f32 v[46:47], v[46:47], v[86:87] op_sel_hi:[1,0]
	v_pk_mul_f32 v[44:45], v[44:45], v[86:87] op_sel_hi:[1,0]
	v_pk_mul_f32 v[42:43], v[42:43], v[86:87] op_sel_hi:[1,0]
	v_pk_mul_f32 v[40:41], v[40:41], v[86:87] op_sel_hi:[1,0]
	v_pk_mul_f32 v[38:39], v[38:39], v[86:87] op_sel_hi:[1,0]
	v_pk_mul_f32 v[36:37], v[36:37], v[86:87] op_sel_hi:[1,0]
	v_pk_mul_f32 v[34:35], v[34:35], v[86:87] op_sel_hi:[1,0]
	v_pk_mul_f32 v[32:33], v[32:33], v[86:87] op_sel_hi:[1,0]
	v_pk_mul_f32 v[14:15], v[14:15], v[86:87] op_sel_hi:[1,0]
	v_pk_mul_f32 v[12:13], v[12:13], v[86:87] op_sel_hi:[1,0]
	v_pk_mul_f32 v[10:11], v[10:11], v[86:87] op_sel_hi:[1,0]
	v_pk_mul_f32 v[8:9], v[8:9], v[86:87] op_sel_hi:[1,0]
	v_pk_mul_f32 v[6:7], v[6:7], v[86:87] op_sel_hi:[1,0]
	v_pk_mul_f32 v[4:5], v[4:5], v[86:87] op_sel_hi:[1,0]
	v_pk_mul_f32 v[2:3], v[2:3], v[86:87] op_sel_hi:[1,0]
	v_pk_mul_f32 v[0:1], v[0:1], v[86:87] op_sel_hi:[1,0]
	v_lshl_add_u64 v[86:87], v[84:85], 0, v[68:69]
	s_mov_b32 s0, 0x100000
	v_add_co_u32_e32 v84, vcc, s0, v86
	global_load_dwordx4 v[92:95], v[86:87], off
	s_nop 0
	v_addc_co_u32_e32 v85, vcc, 0, v87, vcc
	global_load_dwordx4 v[96:99], v[84:85], off
	ds_read_b128 v[88:91], v77 offset:9984
	ds_read_b128 v[100:103], v77 offset:5376
	ds_read_b128 v[104:107], v77 offset:5408
	s_waitcnt vmcnt(1) lgkmcnt(1)
; #define LAS __attribute__((address_space(3)))
; __device__ __forceinline__ void mlstm_stage_c(LAS unsigned char* lds, const bf16_t* QKO, const bf16_t* KVT, const float* G, const float* gbias, const bf16_t* DC, const float* DN, ...
;     ...
;         { const bf16_t* v0p = KVT + (size_t)(h * 512 + wave * 64 + r32) * M + t0 + hi * 8; const bf16_t* v1p = v0p + (size_t)32 * M;
; #pragma unroll
;           for (int ks = 0; ks < 4; ++ks) { const bf16x8 b0 = *(const LAS bf16x8*)(sW + r32 * 144 + ks * 32 + hi * 16), b1 = *(const LAS bf16x8*)(sW + (32 + r32) * 144 + ks * 32 + hi * 16);
;               const bf16x8 a0 = *(const bf16x8*)(v0p + ks * 16), a1 = *(const bf16x8*)(v1p + ks * 16);
;               acc[0][0] = __builtin_amdgcn_mfma_f32_32x32x16_bf16(a0, b0, acc[0][0], 0, 0, 0); acc[0][1] = __builtin_amdgcn_mfma_f32_32x32x16_bf16(a0, b1, acc[0][1], 0, 0, 0);
;               acc[1][0] = __builtin_amdgcn_mfma_f32_32x32x16_bf16(a1, b0, acc[1][0], 0, 0, 0); acc[1][1] = __builtin_amdgcn_mfma_f32_32x32x16_bf16(a1, b1, acc[1][1], 0, 0, 0); } }
;         __syncthreads();
; #pragma unroll
;         for (int tb = 0; tb < 2; ++tb) { const float dinv = sDinv[tb * 32 + r32]; float ss = 0.f;
; #pragma unroll
;             for (int vb = 0; vb < 2; ++vb) { acc[vb][tb] *= dinv;
; #pragma unroll
;                 for (int r = 0; r < 16; ++r) ss += acc[vb][tb][r] * acc[vb][tb][r]; }
;             ss += __shfl_xor(ss, 32);
;             if (hi == 0) sSsq[wave * 64 + tb * 32 + r32] = ss; }
	v_mfma_f32_32x32x16_bf16 v[48:63], v[92:95], v[100:103], v[48:63]
	v_mfma_f32_32x32x16_bf16 v[32:47], v[92:95], v[88:91], v[32:47]
	s_waitcnt vmcnt(0)
	v_mfma_f32_32x32x16_bf16 v[16:31], v[96:99], v[100:103], v[16:31]
	v_mfma_f32_32x32x16_bf16 v[0:15], v[96:99], v[88:91], v[0:15]
	ds_read_b128 v[88:91], v77 offset:10016
	global_load_dwordx4 v[92:95], v[86:87], off offset:32
	global_load_dwordx4 v[96:99], v[84:85], off offset:32
	s_waitcnt vmcnt(1) lgkmcnt(1)
	v_mfma_f32_32x32x16_bf16 v[48:63], v[92:95], v[104:107], v[48:63]
	s_waitcnt lgkmcnt(0)
	v_mfma_f32_32x32x16_bf16 v[32:47], v[92:95], v[88:91], v[32:47]
	s_waitcnt vmcnt(0)
	v_mfma_f32_32x32x16_bf16 v[16:31], v[96:99], v[104:107], v[16:31]
	v_mfma_f32_32x32x16_bf16 v[0:15], v[96:99], v[88:91], v[0:15]
	ds_read_b128 v[88:91], v77 offset:5440
	ds_read_b128 v[92:95], v77 offset:10048
	global_load_dwordx4 v[96:99], v[86:87], off offset:64
	global_load_dwordx4 v[100:103], v[84:85], off offset:64
	s_waitcnt vmcnt(1) lgkmcnt(1)
	v_mfma_f32_32x32x16_bf16 v[48:63], v[96:99], v[88:91], v[48:63]
	s_waitcnt lgkmcnt(0)
	v_mfma_f32_32x32x16_bf16 v[32:47], v[96:99], v[92:95], v[32:47]
	s_waitcnt vmcnt(0)
	v_mfma_f32_32x32x16_bf16 v[16:31], v[100:103], v[88:91], v[16:31]
	v_mfma_f32_32x32x16_bf16 v[0:15], v[100:103], v[92:95], v[0:15]
	ds_read_b128 v[88:91], v77 offset:5472
	ds_read_b128 v[92:95], v77 offset:10080
	global_load_dwordx4 v[96:99], v[86:87], off offset:96
	s_nop 0
	global_load_dwordx4 v[84:87], v[84:85], off offset:96
	s_waitcnt lgkmcnt(0)
	s_barrier
	s_waitcnt vmcnt(1)
	v_mfma_f32_32x32x16_bf16 v[48:63], v[96:99], v[88:91], v[48:63]
	s_waitcnt vmcnt(0)
	v_mfma_f32_32x32x16_bf16 v[16:31], v[84:87], v[88:91], v[16:31]
	ds_read_b32 v90, v141 offset:1024
	s_waitcnt lgkmcnt(0)
	s_nop 7
	v_mul_f32_e64 v104, v48, v90
	v_mul_f32_e64 v105, v49, v90
	v_mul_f32_e64 v102, v50, v90
	v_mul_f32_e64 v103, v51, v90
	v_mfma_f32_32x32x16_bf16 v[32:47], v[96:99], v[92:95], v[32:47]
	v_mul_f32_e64 v96, v56, v90
	v_mul_f32_e64 v97, v57, v90
	v_mul_f32_e32 v56, v105, v105
	v_fmac_f32_e32 v56, v104, v104
	v_fmac_f32_e32 v56, v102, v102
	v_pk_mul_f32 v[100:101], v[52:53], v[90:91] op_sel_hi:[1,0]
	v_fmac_f32_e32 v56, v103, v103
	v_fmac_f32_e32 v56, v100, v100
	v_pk_mul_f32 v[98:99], v[54:55], v[90:91] op_sel_hi:[1,0]
	v_fmac_f32_e32 v56, v101, v101
	v_fmac_f32_e32 v56, v98, v98
	v_fmac_f32_e32 v56, v99, v99
	v_fmac_f32_e32 v56, v96, v96
	v_mfma_f32_32x32x16_bf16 v[0:15], v[84:87], v[92:95], v[0:15]
	v_mul_f32_e64 v94, v58, v90
	v_mul_f32_e64 v95, v59, v90
	v_fmac_f32_e32 v56, v97, v97
	v_fmac_f32_e32 v56, v94, v94
	v_mul_f32_e64 v92, v60, v90
	v_mul_f32_e64 v93, v61, v90
	v_fmac_f32_e32 v56, v95, v95
	v_fmac_f32_e32 v56, v92, v92
	v_pk_mul_f32 v[88:89], v[62:63], v[90:91] op_sel_hi:[1,0]
	v_fmac_f32_e32 v56, v93, v93
	v_fmac_f32_e32 v56, v88, v88
	v_fmac_f32_e32 v56, v89, v89
	v_pk_mul_f32 v[48:49], v[30:31], v[90:91] op_sel_hi:[1,0]
	v_pk_mul_f32 v[50:51], v[28:29], v[90:91] op_sel_hi:[1,0]
	v_pk_mul_f32 v[52:53], v[26:27], v[90:91] op_sel_hi:[1,0]
	v_pk_mul_f32 v[54:55], v[24:25], v[90:91] op_sel_hi:[1,0]
	v_pk_mul_f32 v[62:63], v[22:23], v[90:91] op_sel_hi:[1,0]
	v_pk_mul_f32 v[84:85], v[20:21], v[90:91] op_sel_hi:[1,0]
	v_pk_mul_f32 v[86:87], v[18:19], v[90:91] op_sel_hi:[1,0]
	v_pk_mul_f32 v[90:91], v[16:17], v[90:91] op_sel_hi:[1,0]
	s_nop 0
	v_fmac_f32_e32 v56, v90, v90
	v_fmac_f32_e32 v56, v91, v91
	v_fmac_f32_e32 v56, v86, v86
	v_fmac_f32_e32 v56, v87, v87
	v_fmac_f32_e32 v56, v84, v84
	v_fmac_f32_e32 v56, v85, v85
	v_fmac_f32_e32 v56, v62, v62
	v_fmac_f32_e32 v56, v63, v63
	v_fmac_f32_e32 v56, v54, v54
	v_fmac_f32_e32 v56, v55, v55
	v_fmac_f32_e32 v56, v52, v52
	v_fmac_f32_e32 v56, v53, v53
	v_fmac_f32_e32 v56, v50, v50
	v_fmac_f32_e32 v56, v51, v51
	v_fmac_f32_e32 v56, v48, v48
	v_fmac_f32_e32 v56, v49, v49
	ds_bpermute_b32 v16, v123, v56
	s_and_saveexec_b64 s[0:1], s[16:17]
	s_cbranch_execz .LBB0_824
	s_waitcnt lgkmcnt(0)
	v_add_f32_e32 v16, v56, v16
	ds_write_b32 v124, v16 offset:3328
